# one static s_setprio 1 for waves 4-7 before each MLA attention K-loop (reset at loop exit)
# speedup vs baseline: 1.0039x; 1.0039x over previous
.LBB0_554:
	s_or_b64 exec, exec, s[12:13]
	s_lshl_b32 s12, s57, 20
	v_ashrrev_i32_e32 v16, 3, v8
	s_add_u32 s12, s45, s12
	v_ashrrev_i32_e32 v12, 3, v6
	v_ashrrev_i32_e32 v17, 31, v16
	s_addc_u32 s13, s46, 0
	v_ashrrev_i32_e32 v13, 31, v12
	v_lshlrev_b64 v[18:19], 13, v[16:17]
	v_lshlrev_b32_e32 v0, 4, v6
	v_lshlrev_b64 v[14:15], 13, v[12:13]
	v_lshl_add_u64 v[18:19], s[12:13], 0, v[18:19]
	v_and_b32_e32 v0, 0x70, v0
	v_lshl_add_u64 v[14:15], s[12:13], 0, v[14:15]
	v_lshl_add_u64 v[174:175], v[18:19], 0, v[0:1]
	v_lshl_add_u64 v[172:173], v[14:15], 0, v[0:1]
	global_load_dwordx4 v[164:167], v[174:175], off
	global_load_dwordx4 v[168:171], v[172:173], off
	v_add_u32_e32 v186, v7, v3
	v_add_u32_e32 v17, 0, v0
	v_mul_lo_u32 v0, v186, 20
	s_movk_i32 s12, 0x150
	v_add_u32_e32 v187, v10, v9
	v_and_b32_e32 v13, 31, v6
	v_sub_u32_e32 v0, v6, v0
	v_mul_lo_u32 v6, v187, s12
	v_mul_lo_u32 v3, v186, s12
	v_add_u32_e32 v20, 0, v6
	v_mul_lo_u32 v6, v185, s12
	s_movk_i32 s12, 0x88
	v_add_u32_e32 v18, 0, v3
	v_mul_lo_u32 v3, v187, 20
	v_add_u32_e32 v22, 0, v6
	v_mul_lo_u32 v24, v12, s12
	v_mul_lo_u32 v16, v16, s12
	v_lshlrev_b32_e32 v6, 3, v0
	v_readlane_b32 s12, v253, 29
	v_sub_u32_e32 v3, v8, v3
	v_ashrrev_i32_e32 v7, 31, v6
	v_readlane_b32 s13, v253, 30
	s_mov_b32 s12, 64
	v_lshl_add_u64 v[176:177], v[6:7], 1, s[22:23]
	v_lshlrev_b32_e32 v6, 3, v3
	v_writelane_b32 v253, s12, 29
	v_lshlrev_b32_e32 v19, 4, v0
	v_lshlrev_b32_e32 v21, 4, v3
	v_lshlrev_b32_e32 v23, 4, v11
	v_ashrrev_i32_e32 v7, 31, v6
	v_mul_u32_u24_e32 v0, 0x150, v13
	v_lshl_add_u32 v25, v182, 3, 0
	v_mul_u32_u24_e32 v26, 0x88, v13
	v_writelane_b32 v253, s13, 30
	v_mov_b32_e32 v14, v1
	v_mov_b32_e32 v15, v1
	s_movk_i32 s12, 0x5400
	v_lshl_add_u64 v[178:179], v[6:7], 1, s[22:23]
	v_lshl_add_u64 v[180:181], v[4:5], 1, s[22:23]
	v_add3_u32 v188, 0, v0, v2
	v_mov_b32_e32 v0, v1
	v_mov_b32_e32 v2, v1
	v_mov_b32_e32 v3, v1
	v_mov_b32_e32 v4, v1
	v_mov_b32_e32 v5, v1
	v_mov_b32_e32 v6, v1
	v_mov_b32_e32 v7, v1
	v_mov_b32_e32 v8, v1
	v_mov_b32_e32 v9, v1
	v_mov_b32_e32 v10, v1
	v_mov_b32_e32 v11, v1
	v_mov_b32_e32 v12, v1
	v_mov_b32_e32 v13, v1
	v_add_u32_e32 v189, v18, v19
	v_add_u32_e32 v190, v20, v21
	v_add_u32_e32 v191, v22, v23
	s_waitcnt vmcnt(3)
	v_add3_u32 v192, v17, v24, s12
	v_add3_u32 v193, v17, v16, s12
	v_add_u32_e32 v194, v25, v26
	v_mov_b64_e32 v[30:31], v[14:15]
	v_mov_b64_e32 v[46:47], v[14:15]
	v_mov_b64_e32 v[62:63], v[14:15]
	v_mov_b64_e32 v[78:79], v[14:15]
	s_sub_i32 s57, 64, s33
	s_mov_b32 s58, 0
	v_mov_b32_e32 v195, 0xf149f2ca
	v_mov_b32_e32 v184, 0
	v_mov_b64_e32 v[28:29], v[12:13]
	v_mov_b64_e32 v[26:27], v[10:11]
	v_mov_b64_e32 v[24:25], v[8:9]
	v_mov_b64_e32 v[22:23], v[6:7]
	v_mov_b64_e32 v[20:21], v[4:5]
	v_mov_b64_e32 v[18:19], v[2:3]
	v_mov_b64_e32 v[16:17], v[0:1]
	v_mov_b64_e32 v[44:45], v[12:13]
	v_mov_b64_e32 v[42:43], v[10:11]
	v_mov_b64_e32 v[40:41], v[8:9]
	v_mov_b64_e32 v[38:39], v[6:7]
	v_mov_b64_e32 v[36:37], v[4:5]
	v_mov_b64_e32 v[34:35], v[2:3]
	v_mov_b64_e32 v[32:33], v[0:1]
	v_mov_b64_e32 v[60:61], v[12:13]
	v_mov_b64_e32 v[58:59], v[10:11]
	v_mov_b64_e32 v[56:57], v[8:9]
	v_mov_b64_e32 v[54:55], v[6:7]
	v_mov_b64_e32 v[52:53], v[4:5]
	v_mov_b64_e32 v[50:51], v[2:3]
	v_mov_b64_e32 v[48:49], v[0:1]
	v_mov_b64_e32 v[76:77], v[12:13]
	v_mov_b64_e32 v[74:75], v[10:11]
	v_mov_b64_e32 v[72:73], v[8:9]
	v_mov_b64_e32 v[70:71], v[6:7]
	v_mov_b64_e32 v[68:69], v[4:5]
	v_mov_b64_e32 v[66:67], v[2:3]
	v_mov_b64_e32 v[64:65], v[0:1]
	v_readfirstlane_b32 s99, v201
	s_nop 3
	s_cmpk_lt_u32 s99, 0x100
	s_cbranch_scc1 .Lprio_skip_556
	s_setprio 1

.LBB0_573:
	s_setprio 0
	s_mov_b64 s[6:7], 0
	s_mov_b64 s[22:23], 0
	s_and_saveexec_b64 s[8:9], vcc
	s_xor_b64 s[8:9], exec, s[8:9]
	s_cbranch_execz .LBB0_575
	v_and_b32_e32 v2, 64, v218
	v_xor_b32_e32 v0, 32, v218
	v_add_u32_e32 v2, 64, v2
	v_cmp_lt_i32_e32 vcc, v0, v2
	s_mov_b64 s[22:23], exec
	s_nop 0
	v_cndmask_b32_e32 v0, v218, v0, vcc
	v_lshlrev_b32_e32 v0, 2, v0
	ds_bpermute_b32 v0, v0, v184

.LBB0_586:
	s_or_b64 exec, exec, s[26:27]
	s_mul_i32 s24, s33, 0x84000
	s_mul_hi_u32 s25, s33, 0x84000
	s_add_u32 s24, s51, s24
	s_addc_u32 s25, s52, s25
	v_ashrrev_i32_e32 v15, 3, v8
	v_mov_b64_e32 v[16:17], s[24:25]
	s_movk_i32 s26, 0x1080
	v_ashrrev_i32_e32 v20, 3, v10
	v_lshlrev_b32_e32 v0, 4, v8
	v_mad_i64_i32 v[18:19], s[24:25], v15, s26, v[16:17]
	v_mad_i64_i32 v[16:17], s[24:25], v20, s26, v[16:17]
	v_and_b32_e32 v0, 0x70, v0
	v_lshl_add_u64 v[16:17], v[16:17], 0, v[0:1]
	v_lshl_add_u64 v[18:19], v[18:19], 0, v[0:1]
	global_load_dwordx4 v[164:167], v[16:17], off
	global_load_dwordx4 v[168:171], v[18:19], off
	v_mad_i64_i32 v[16:17], s[24:25], v15, s26, 0
	v_mad_i64_i32 v[18:19], s[24:25], v20, s26, 0
	v_add_u32_e32 v23, v9, v3
	v_mul_lo_u32 v3, v23, 20
	s_movk_i32 s24, 0x150
	v_and_b32_e32 v21, 31, v8
	v_sub_u32_e32 v3, v8, v3
	v_mul_lo_u32 v8, v23, s24
	v_add_u32_e32 v26, v12, v11
	v_add_u32_e32 v24, 0, v8
	v_mul_lo_u32 v8, v26, 20
	v_sub_u32_e32 v10, v10, v8
	v_mul_lo_u32 v8, v26, s24
	v_add_u32_e32 v27, 0, v8
	v_mul_lo_u32 v8, v13, s24
	s_movk_i32 s24, 0x88
	v_mul_lo_u32 v31, v15, s24
	v_mul_lo_u32 v20, v20, s24
	s_add_u32 s24, s58, 0x1f44d000
	v_lshlrev_b32_e32 v25, 4, v3
	v_add_u32_e32 v29, 0, v8
	v_lshlrev_b32_e32 v8, 3, v3
	v_mul_u32_u24_e32 v3, 0x150, v21
	s_addc_u32 s25, s57, 0
	v_lshlrev_b32_e32 v28, 4, v10
	v_lshlrev_b32_e32 v10, 3, v10
	v_add3_u32 v185, 0, v3, v2
	v_mov_b64_e32 v[2:3], s[24:25]
	s_movk_i32 s57, 0x140
	v_ashrrev_i32_e32 v11, 31, v10
	v_mad_i64_i32 v[12:13], s[26:27], v23, s57, v[2:3]
	v_mad_i64_i32 v[2:3], s[26:27], v26, s57, v[2:3]
	v_lshl_add_u64 v[174:175], v[10:11], 1, v[2:3]
	v_lshl_add_u64 v[2:3], s[24:25], 0, v[6:7]
	v_lshl_add_u64 v[176:177], v[4:5], 1, v[2:3]
	v_mov_b32_e32 v2, 0x84000
	v_mad_u64_u32 v[178:179], s[24:25], s33, v2, v[18:19]
	v_mad_u64_u32 v[180:181], s[24:25], s33, v2, v[16:17]
	v_add_u32_e32 v22, 0, v0
	v_lshlrev_b32_e32 v30, 4, v14
	v_ashrrev_i32_e32 v9, 31, v8
	v_lshl_add_u32 v32, v182, 3, 0
	v_mul_u32_u24_e32 v21, 0x88, v21
	v_mov_b32_e32 v14, v1
	v_mov_b32_e32 v15, v1
	s_movk_i32 s24, 0x5400
	v_lshl_add_u64 v[172:173], v[8:9], 1, v[12:13]
	v_or_b32_e32 v178, v178, v0
	v_or_b32_e32 v180, v180, v0
	v_mov_b32_e32 v0, v1
	v_mov_b32_e32 v2, v1
	v_mov_b32_e32 v3, v1
	v_mov_b32_e32 v4, v1
	v_mov_b32_e32 v5, v1
	v_mov_b32_e32 v6, v1
	v_mov_b32_e32 v7, v1
	v_mov_b32_e32 v8, v1
	v_mov_b32_e32 v9, v1
	v_mov_b32_e32 v10, v1
	v_mov_b32_e32 v11, v1
	v_mov_b32_e32 v12, v1
	v_mov_b32_e32 v13, v1
	v_add_u32_e32 v186, v24, v25
	v_add_u32_e32 v187, v27, v28
	v_add_u32_e32 v188, v29, v30
	v_add3_u32 v189, v22, v31, s24
	v_add3_u32 v190, v22, v20, s24
	v_add_u32_e32 v191, v32, v21
	v_mov_b64_e32 v[30:31], v[14:15]
	v_mov_b64_e32 v[46:47], v[14:15]
	v_mov_b64_e32 v[62:63], v[14:15]
	v_mov_b64_e32 v[78:79], v[14:15]
	s_mov_b32 s26, 0
	s_waitcnt vmcnt(3)
	v_mov_b32_e32 v192, 0xf149f2ca
	v_mov_b32_e32 v184, 0
	v_mov_b64_e32 v[28:29], v[12:13]
	v_mov_b64_e32 v[26:27], v[10:11]
	v_mov_b64_e32 v[24:25], v[8:9]
	v_mov_b64_e32 v[22:23], v[6:7]
	v_mov_b64_e32 v[20:21], v[4:5]
	v_mov_b64_e32 v[18:19], v[2:3]
	v_mov_b64_e32 v[16:17], v[0:1]
	v_mov_b64_e32 v[44:45], v[12:13]
	v_mov_b64_e32 v[42:43], v[10:11]
	v_mov_b64_e32 v[40:41], v[8:9]
	v_mov_b64_e32 v[38:39], v[6:7]
	v_mov_b64_e32 v[36:37], v[4:5]
	v_mov_b64_e32 v[34:35], v[2:3]
	v_mov_b64_e32 v[32:33], v[0:1]
	v_mov_b64_e32 v[60:61], v[12:13]
	v_mov_b64_e32 v[58:59], v[10:11]
	v_mov_b64_e32 v[56:57], v[8:9]
	v_mov_b64_e32 v[54:55], v[6:7]
	v_mov_b64_e32 v[52:53], v[4:5]
	v_mov_b64_e32 v[50:51], v[2:3]
	v_mov_b64_e32 v[48:49], v[0:1]
	v_mov_b64_e32 v[76:77], v[12:13]
	v_mov_b64_e32 v[74:75], v[10:11]
	v_mov_b64_e32 v[72:73], v[8:9]
	v_mov_b64_e32 v[70:71], v[6:7]
	v_mov_b64_e32 v[68:69], v[4:5]
	v_mov_b64_e32 v[66:67], v[2:3]
	v_mov_b64_e32 v[64:65], v[0:1]
	v_readfirstlane_b32 s99, v201
	s_nop 3
	s_cmpk_lt_u32 s99, 0x100
	s_cbranch_scc1 .Lprio_skip_588
	s_setprio 1

.LBB0_604:
	s_setprio 0
	s_and_saveexec_b64 s[8:9], s[6:7]
	s_cbranch_execz .LBB0_606
	v_and_b32_e32 v2, 64, v218
	v_xor_b32_e32 v0, 32, v218
	v_add_u32_e32 v2, 64, v2
	v_cmp_lt_i32_e32 vcc, v0, v2
	s_or_b64 s[22:23], s[22:23], exec
	s_nop 0
	v_cndmask_b32_e32 v0, v218, v0, vcc
	v_lshlrev_b32_e32 v0, 2, v0
	ds_bpermute_b32 v0, v0, v184
